# A-loop diagonal-mask path: MFMA-to-VALU pad restored to 12 wait states (s_nop 5); otherwise identical to the atomic-batch version
# speedup vs baseline: 1.0140x; 1.0140x over previous
; DI f32x16 mfma(bf16x8 a, bf16x8 b, f32x16 c) { return __builtin_amdgcn_mfma_f32_32x32x16_bf16(a, b, c, 0, 0, 0); }
; DI void mask_causal(f32x16& s0, f32x16& s1, int dl) {
; #pragma unroll
;   for (int i = 0; i < 16; ++i) {
;     const int ci = (i & 3) + 8 * (i >> 2);
;     s0[i] = (ci <= dl) ? s0[i] : -INFINITY;
;     s1[i] = (ci + 32 <= dl) ? s1[i] : -INFINITY;
;   }
; }
; DI void diff_softmax_pv(const bf16x8 (&qf)[4], const u16* Ks, const u16* Vs, float& m, f32x4& ls0, f32x4& ls1, bf16x8 ones,
;                         f32x16 (&o)[2][2], float sl2, int dl, bool need_mask, bool first, int r, int h, int rs, const int (&lo)[4]) {
;     ...
;   const float nb = -sl2 * (float)dl - m;
; #pragma unroll
;   for (int i = 0; i < 16; ++i) {
;     const int ci = (i & 3) + 8 * (i >> 2);
;     b0[i] = fmaf(sl2, (float)ci, nb);
;     b1[i] = fmaf(sl2, (float)(ci + 32), nb);
;   }
;   {
;     __builtin_amdgcn_s_setprio(1);
;     f32x16 s0 = mfma(ldsv(Ks + lo[0]), qf[0], b0);
;     f32x16 s1 = mfma(ldsv(Ks + 32 * rs + lo[0]), qf[0], b1);
;     s0 = mfma(ldsv(Ks + lo[1]), qf[1], s0);
;     s1 = mfma(ldsv(Ks + 32 * rs + lo[1]), qf[1], s1);
;     __builtin_amdgcn_s_setprio(0);
;     if (need_mask) mask_causal(s0, s1, dl);
.LBB0_281:
	s_or_b64 exec, exec, s[2:3]
	v_cvt_f32_i32_e32 v66, v207
	s_and_b32 s2, s64, 0x2000
	v_lshl_add_u32 v211, s2, 1, v176
	v_lshl_add_u32 v213, v183, 1, v211
	v_lshl_add_u32 v212, v184, 1, v211
	v_fma_f32 v229, -v178, v66, -v204
	v_lshl_add_u32 v246, v185, 1, v211
	v_lshl_add_u32 v247, v186, 1, v211
	ds_read_b128 v[114:117], v213
	ds_read_b128 v[214:217], v213 offset:4096
	ds_read_b128 v[218:221], v212
	ds_read_b128 v[222:225], v212 offset:4096
	ds_read_b128 v[230:233], v246
	ds_read_b128 v[234:237], v246 offset:4096
	ds_read_b128 v[238:241], v247
	ds_read_b128 v[242:245], v247 offset:4096
	v_cmp_eq_u32_e64 s[38:39], 0, v208
	v_fma_f32 v66, 0, v178, v229
	v_add_f32_e32 v67, v178, v229
	v_fmamk_f32 v68, v178, 0x40000000, v229
	v_fmamk_f32 v69, v178, 0x40400000, v229
	v_fmamk_f32 v70, v178, 0x41000000, v229
	v_fmamk_f32 v71, v178, 0x41100000, v229
	v_fmamk_f32 v72, v178, 0x41200000, v229
	v_fmamk_f32 v73, v178, 0x41300000, v229
	v_fmamk_f32 v74, v178, 0x41800000, v229
	v_fmamk_f32 v75, v178, 0x41880000, v229
	v_fmamk_f32 v76, v178, 0x41900000, v229
	v_fmamk_f32 v77, v178, 0x41980000, v229
	v_fmamk_f32 v78, v178, 0x41c00000, v229
	v_fmamk_f32 v79, v178, 0x41c80000, v229
	v_fmamk_f32 v80, v178, 0x41d00000, v229
	v_fmamk_f32 v81, v178, 0x41d80000, v229
	v_fmamk_f32 v82, v178, 0x42000000, v229
	v_fmamk_f32 v83, v178, 0x42040000, v229
	v_fmamk_f32 v84, v178, 0x42080000, v229
	v_fmamk_f32 v85, v178, 0x420c0000, v229
	v_fmamk_f32 v86, v178, 0x42200000, v229
	v_fmamk_f32 v87, v178, 0x42240000, v229
	v_fmamk_f32 v88, v178, 0x42280000, v229
	v_fmamk_f32 v89, v178, 0x422c0000, v229
	v_fmamk_f32 v90, v178, 0x42400000, v229
	v_fmamk_f32 v91, v178, 0x42440000, v229
	v_fmamk_f32 v92, v178, 0x42480000, v229
	v_fmamk_f32 v93, v178, 0x424c0000, v229
	v_fmamk_f32 v94, v178, 0x42600000, v229
	v_fmamk_f32 v95, v178, 0x42640000, v229
	v_fmamk_f32 v96, v178, 0x42680000, v229
	v_fmamk_f32 v97, v178, 0x426c0000, v229
	s_setprio 1
	s_waitcnt lgkmcnt(6)
	v_mfma_f32_32x32x16_bf16 v[98:113], v[114:117], v[130:133], v[66:81]
	v_mfma_f32_32x32x16_bf16 v[114:129], v[214:217], v[130:133], v[82:97]
	s_waitcnt lgkmcnt(5)
	v_mfma_f32_32x32x16_bf16 v[98:113], v[218:221], v[134:137], v[98:113]
	s_waitcnt lgkmcnt(4)
	v_mfma_f32_32x32x16_bf16 v[114:129], v[222:225], v[134:137], v[114:129]
	s_setprio 0
	s_and_saveexec_b64 s[2:3], s[38:39]
	s_cbranch_execz .LBB0_283
	v_cmp_lt_i32_e32 vcc, -1, v207
	s_nop 5
	v_cndmask_b32_e32 v98, v199, v98, vcc
	v_cmp_lt_i32_e32 vcc, 31, v207
	s_nop 1
	v_cndmask_b32_e32 v114, v199, v114, vcc
	v_cmp_lt_i32_e32 vcc, 0, v207
	s_nop 1
	v_cndmask_b32_e32 v99, v199, v99, vcc
	v_cmp_lt_i32_e32 vcc, 32, v207
	s_nop 1
	v_cndmask_b32_e32 v115, v199, v115, vcc
	v_cmp_lt_i32_e32 vcc, 1, v207
	s_nop 1
	v_cndmask_b32_e32 v100, v199, v100, vcc
	v_cmp_lt_i32_e32 vcc, 33, v207
	s_nop 1
	v_cndmask_b32_e32 v116, v199, v116, vcc
	v_cmp_lt_i32_e32 vcc, 2, v207
	s_nop 1
	v_cndmask_b32_e32 v101, v199, v101, vcc
	v_cmp_lt_i32_e32 vcc, 34, v207
	s_nop 1
	v_cndmask_b32_e32 v117, v199, v117, vcc
	v_cmp_lt_i32_e32 vcc, 7, v207
	s_nop 1
	v_cndmask_b32_e32 v102, v199, v102, vcc
	v_cmp_lt_i32_e32 vcc, 39, v207
	s_nop 1
	v_cndmask_b32_e32 v118, v199, v118, vcc
	v_cmp_lt_i32_e32 vcc, 8, v207
	s_nop 1
	v_cndmask_b32_e32 v103, v199, v103, vcc
	v_cmp_lt_i32_e32 vcc, 40, v207
	s_nop 1
	v_cndmask_b32_e32 v119, v199, v119, vcc
	v_cmp_lt_i32_e32 vcc, 9, v207
	s_nop 1
	v_cndmask_b32_e32 v104, v199, v104, vcc
	v_cmp_lt_i32_e32 vcc, 41, v207
	s_nop 1
	v_cndmask_b32_e32 v120, v199, v120, vcc
	v_cmp_lt_i32_e32 vcc, 10, v207
	s_nop 1
	v_cndmask_b32_e32 v105, v199, v105, vcc
	v_cmp_lt_i32_e32 vcc, 42, v207
	s_nop 1
	v_cndmask_b32_e32 v121, v199, v121, vcc
	v_cmp_lt_i32_e32 vcc, 15, v207
	s_nop 1
	v_cndmask_b32_e32 v106, v199, v106, vcc
	v_cmp_lt_i32_e32 vcc, 47, v207
	s_nop 1
	v_cndmask_b32_e32 v122, v199, v122, vcc
	v_cmp_lt_i32_e32 vcc, 16, v207
	s_nop 1
	v_cndmask_b32_e32 v107, v199, v107, vcc
	v_cmp_lt_i32_e32 vcc, 48, v207
	s_nop 1
	v_cndmask_b32_e32 v123, v199, v123, vcc
	v_cmp_lt_i32_e32 vcc, 17, v207
	s_nop 1
	v_cndmask_b32_e32 v108, v199, v108, vcc
	v_cmp_lt_i32_e32 vcc, 49, v207
	s_nop 1
	v_cndmask_b32_e32 v124, v199, v124, vcc
	v_cmp_lt_i32_e32 vcc, 18, v207
	s_nop 1
	v_cndmask_b32_e32 v109, v199, v109, vcc
	v_cmp_lt_i32_e32 vcc, 50, v207
	s_nop 1
	v_cndmask_b32_e32 v125, v199, v125, vcc
	v_cmp_lt_i32_e32 vcc, 23, v207
	s_nop 1
	v_cndmask_b32_e32 v110, v199, v110, vcc
	v_cmp_lt_i32_e32 vcc, 55, v207
	s_nop 1
	v_cndmask_b32_e32 v126, v199, v126, vcc
	v_cmp_lt_i32_e32 vcc, 24, v207
	s_nop 1
	v_cndmask_b32_e32 v111, v199, v111, vcc
	v_cmp_lt_i32_e32 vcc, 56, v207
	s_nop 1
	v_cndmask_b32_e32 v127, v199, v127, vcc
	v_cmp_lt_i32_e32 vcc, 25, v207
	s_nop 1
	v_cndmask_b32_e32 v112, v199, v112, vcc
	v_cmp_lt_i32_e32 vcc, 57, v207
	s_nop 1
	v_cndmask_b32_e32 v128, v199, v128, vcc
	v_cmp_lt_i32_e32 vcc, 26, v207
	s_nop 1
	v_cndmask_b32_e32 v113, v199, v113, vcc
	v_cmp_lt_i32_e32 vcc, 58, v207
	s_nop 1
	v_cndmask_b32_e32 v129, v199, v129, vcc
